# grid barrier: last-arriving XCD leader releases all XCD generation words directly (one polling hop fewer)
# baseline (speedup 1.0000x reference)
; DI unsigned xb_add(unsigned* p, unsigned v) { return __hip_atomic_fetch_add(p, v, __ATOMIC_RELAXED, __HIP_MEMORY_SCOPE_AGENT); }
; DI void xcd_barrier(const XcdBarrier& b) {
;     ...
;             __builtin_amdgcn_fence(__ATOMIC_ACQUIRE, "agent");
;             xb_add(&bar[XB_XGEN(b.x)], 1u);
;             asm volatile("s_waitcnt vmcnt(0)" ::: "memory");
.LBB0_67:
	s_or_b64 exec, exec, s[18:19]
	v_readlane_b32 s18, v253, 48
	v_readlane_b32 s19, v253, 49
	s_waitcnt vmcnt(0) lgkmcnt(0)
	buffer_inv sc1
	v_mov_b64_e32 v[2:3], s[18:19]
	s_waitcnt vmcnt(0)

; DI unsigned xb_ld(unsigned* p)              { return __hip_atomic_load(p, __ATOMIC_RELAXED, __HIP_MEMORY_SCOPE_AGENT); }
; DI unsigned xb_add(unsigned* p, unsigned v) { return __hip_atomic_fetch_add(p, v, __ATOMIC_RELAXED, __HIP_MEMORY_SCOPE_AGENT); }
; #define XB_SPIN(cond, bar) do { unsigned _sp = 0; while (cond) { __builtin_amdgcn_s_sleep(1); \
;     if ((++_sp & 255u) == 0u) { if (xb_ld(&(bar)[XB_TMO])) break; if (_sp > XB_SPIN_CAP) { atomicAdd(&(bar)[XB_TMO], 1u); break; } } } } while (0)
; DI void xcd_barrier(const XcdBarrier& b) {
;     ...
;         const unsigned old = xb_add(&bar[XB_XSUB(b.x)], 1u);
;         const unsigned gen = old / nloc;
;         if (old + 1u == (gen + 1u) * nloc) {
;             __builtin_amdgcn_fence(__ATOMIC_RELEASE, "agent");
;             asm volatile("s_waitcnt vmcnt(0)" ::: "memory");
;             const unsigned og = xb_add(&bar[XB_TOP], 1u);
;             const unsigned tg = og / nx;
;             if (og + 1u == (tg + 1u) * nx) xb_add(&bar[XB_TOPGEN], 1u);
;             else XB_SPIN(xb_ld(&bar[XB_TOPGEN]) == tg, bar);
.LBB0_106:
	s_andn2_saveexec_b64 s[18:19], s[18:19]
	s_cbranch_execz .LBB0_122
	v_readlane_b32 s18, v253, 50
	v_readlane_b32 s19, v253, 51
	buffer_wbl2 sc1
	s_waitcnt vmcnt(0)
	v_cvt_f32_u32_e32 v3, v2
	v_mov_b64_e32 v[4:5], s[18:19]
	flat_atomic_add v1, v[4:5], v223 sc0
	v_sub_u32_e32 v4, 0, v2
	v_rcp_iflag_f32_e32 v3, v3
	s_mov_b64 s[20:21], -1
	v_mul_f32_e32 v3, 0x4f7ffffe, v3
	v_cvt_u32_f32_e32 v3, v3
	v_mul_lo_u32 v4, v4, v3
	v_mul_hi_u32 v4, v3, v4
	v_add_u32_e32 v3, v3, v4
	s_waitcnt vmcnt(0) lgkmcnt(0)
	v_mul_hi_u32 v3, v1, v3
	v_mul_lo_u32 v5, v3, v2
	v_add_u32_e32 v4, 1, v1
	v_sub_u32_e32 v1, v1, v5
	v_add_u32_e32 v6, 1, v3
	v_cmp_ge_u32_e32 vcc, v1, v2
	v_sub_u32_e32 v5, v1, v2
	s_nop 0
	v_cndmask_b32_e32 v3, v3, v6, vcc
	v_cndmask_b32_e32 v1, v1, v5, vcc
	v_add_u32_e32 v5, 1, v3
	v_cmp_ge_u32_e32 vcc, v1, v2
	s_nop 1
	v_cndmask_b32_e32 v1, v3, v5, vcc
	v_mad_u64_u32 v[2:3], s[18:19], v2, v1, v[2:3]
	v_readlane_b32 s18, v253, 52
	v_readlane_b32 s19, v253, 53
	v_cmp_ne_u32_e32 vcc, v4, v2
	s_nop 0
	v_mov_b64_e32 v[2:3], s[18:19]
	s_and_saveexec_b64 s[18:19], vcc
	s_cbranch_execnz .Lxb_nl_0
	s_mov_b64 exec, s[18:19]
	v_add_co_u32_e32 v4, vcc, 0xffffef00, v2
	s_nop 1
	v_addc_co_u32_e32 v5, vcc, -1, v3, vcc
	s_nop 1
	global_atomic_add v[4:5], v223, off
	global_atomic_add v[4:5], v223, off offset:256
	global_atomic_add v[4:5], v223, off offset:512
	global_atomic_add v[4:5], v223, off offset:768
	global_atomic_add v[4:5], v223, off offset:1024
	global_atomic_add v[4:5], v223, off offset:1280
	global_atomic_add v[4:5], v223, off offset:1536
	global_atomic_add v[4:5], v223, off offset:1792
	global_atomic_add v[4:5], v223, off offset:2048
	global_atomic_add v[4:5], v223, off offset:2304
	global_atomic_add v[4:5], v223, off offset:2560
	global_atomic_add v[4:5], v223, off offset:2816
	global_atomic_add v[4:5], v223, off offset:3072
	global_atomic_add v[4:5], v223, off offset:3328
	global_atomic_add v[4:5], v223, off offset:3584
	global_atomic_add v[4:5], v223, off offset:3840
	s_mov_b64 exec, 0
	s_branch .LBB0_119
.Lxb_nl_0:
	v_readlane_b32 s20, v253, 48
	v_readlane_b32 s21, v253, 49
	s_mov_b64 s[22:23], 0
	s_nop 0
	v_mov_b64_e32 v[2:3], s[20:21]
	flat_load_dword v2, v[2:3] sc1
	s_waitcnt vmcnt(0) lgkmcnt(0)
	v_cmp_eq_u32_e32 vcc, v2, v1
	s_and_saveexec_b64 s[20:21], vcc
	s_cbranch_execz .LBB0_118
	s_mov_b32 s2, 1
	s_branch .LBB0_111

; DI unsigned xb_ld(unsigned* p)              { return __hip_atomic_load(p, __ATOMIC_RELAXED, __HIP_MEMORY_SCOPE_AGENT); }
; DI unsigned xb_add(unsigned* p, unsigned v) { return __hip_atomic_fetch_add(p, v, __ATOMIC_RELAXED, __HIP_MEMORY_SCOPE_AGENT); }
; #define XB_SPIN(cond, bar) do { unsigned _sp = 0; while (cond) { __builtin_amdgcn_s_sleep(1); \
;     if ((++_sp & 255u) == 0u) { if (xb_ld(&(bar)[XB_TMO])) break; if (_sp > XB_SPIN_CAP) { atomicAdd(&(bar)[XB_TMO], 1u); break; } } } } while (0)
; DI void xcd_barrier(const XcdBarrier& b) {
;     ...
;             if (og + 1u == (tg + 1u) * nx) xb_add(&bar[XB_TOPGEN], 1u);
;             else XB_SPIN(xb_ld(&bar[XB_TOPGEN]) == tg, bar);
.LBB0_116:
	v_readlane_b32 s24, v253, 48
	v_readlane_b32 s25, v253, 49
	s_add_i32 s2, s2, 1
	s_or_b64 s[30:31], s[30:31], exec
	v_mov_b64_e32 v[2:3], s[24:25]
	flat_load_dword v2, v[2:3] sc1
	s_waitcnt vmcnt(0) lgkmcnt(0)
	v_cmp_ne_u32_e32 vcc, v2, v1
	s_orn2_b64 s[28:29], vcc, exec
	s_branch .LBB0_110

; DI unsigned xb_ld(unsigned* p)              { return __hip_atomic_load(p, __ATOMIC_RELAXED, __HIP_MEMORY_SCOPE_AGENT); }
; DI unsigned xb_add(unsigned* p, unsigned v) { return __hip_atomic_fetch_add(p, v, __ATOMIC_RELAXED, __HIP_MEMORY_SCOPE_AGENT); }
; #define XB_SPIN(cond, bar) do { unsigned _sp = 0; while (cond) { __builtin_amdgcn_s_sleep(1); \
;     if ((++_sp & 255u) == 0u) { if (xb_ld(&(bar)[XB_TMO])) break; if (_sp > XB_SPIN_CAP) { atomicAdd(&(bar)[XB_TMO], 1u); break; } } } } while (0)
; DI void xcd_barrier(const XcdBarrier& b) {
;     ...
;         const unsigned old = xb_add(&bar[XB_XSUB(b.x)], 1u);
;         const unsigned gen = old / nloc;
;         if (old + 1u == (gen + 1u) * nloc) {
;             __builtin_amdgcn_fence(__ATOMIC_RELEASE, "agent");
;             asm volatile("s_waitcnt vmcnt(0)" ::: "memory");
;             const unsigned og = xb_add(&bar[XB_TOP], 1u);
;             const unsigned tg = og / nx;
;             if (og + 1u == (tg + 1u) * nx) xb_add(&bar[XB_TOPGEN], 1u);
;             else XB_SPIN(xb_ld(&bar[XB_TOPGEN]) == tg, bar);
.LBB0_219:
	s_andn2_saveexec_b64 s[0:1], s[18:19]
	s_cbranch_execz .LBB0_235
	v_readlane_b32 s0, v253, 50
	v_readlane_b32 s1, v253, 51
	buffer_wbl2 sc1
	s_waitcnt vmcnt(0)
	v_cvt_f32_u32_e32 v1, v2
	v_mov_b64_e32 v[4:5], s[0:1]
	flat_atomic_add v3, v[4:5], v223 sc0
	v_sub_u32_e32 v4, 0, v2
	v_rcp_iflag_f32_e32 v1, v1
	s_mov_b64 s[22:23], -1
	v_mul_f32_e32 v1, 0x4f7ffffe, v1
	v_cvt_u32_f32_e32 v1, v1
	v_mul_lo_u32 v4, v4, v1
	v_mul_hi_u32 v4, v1, v4
	v_add_u32_e32 v1, v1, v4
	s_waitcnt vmcnt(0) lgkmcnt(0)
	v_mul_hi_u32 v1, v3, v1
	v_mul_lo_u32 v4, v1, v2
	v_sub_u32_e32 v4, v3, v4
	v_cmp_ge_u32_e32 vcc, v4, v2
	v_add_u32_e32 v5, 1, v1
	s_nop 0
	v_cndmask_b32_e32 v1, v1, v5, vcc
	v_sub_u32_e32 v5, v4, v2
	v_cndmask_b32_e32 v4, v4, v5, vcc
	v_cmp_ge_u32_e32 vcc, v4, v2
	v_add_u32_e32 v4, 1, v1
	s_nop 0
	v_cndmask_b32_e32 v1, v1, v4, vcc
	v_add_u32_e32 v4, 1, v3
	v_mad_u64_u32 v[2:3], s[0:1], v2, v1, v[2:3]
	v_readlane_b32 s0, v253, 52
	v_readlane_b32 s1, v253, 53
	v_cmp_ne_u32_e32 vcc, v4, v2
	s_nop 0
	v_mov_b64_e32 v[2:3], s[0:1]
	s_and_saveexec_b64 s[18:19], vcc
	s_cbranch_execnz .Lxb_nl_1
	s_mov_b64 exec, s[18:19]
	v_add_co_u32_e32 v4, vcc, 0xffffef00, v2
	s_nop 1
	v_addc_co_u32_e32 v5, vcc, -1, v3, vcc
	s_nop 1
	global_atomic_add v[4:5], v223, off
	global_atomic_add v[4:5], v223, off offset:256
	global_atomic_add v[4:5], v223, off offset:512
	global_atomic_add v[4:5], v223, off offset:768
	global_atomic_add v[4:5], v223, off offset:1024
	global_atomic_add v[4:5], v223, off offset:1280
	global_atomic_add v[4:5], v223, off offset:1536
	global_atomic_add v[4:5], v223, off offset:1792
	global_atomic_add v[4:5], v223, off offset:2048
	global_atomic_add v[4:5], v223, off offset:2304
	global_atomic_add v[4:5], v223, off offset:2560
	global_atomic_add v[4:5], v223, off offset:2816
	global_atomic_add v[4:5], v223, off offset:3072
	global_atomic_add v[4:5], v223, off offset:3328
	global_atomic_add v[4:5], v223, off offset:3584
	global_atomic_add v[4:5], v223, off offset:3840
	s_mov_b64 exec, 0
	s_branch .LBB0_232
.Lxb_nl_1:
	v_readlane_b32 s0, v253, 48
	v_readlane_b32 s1, v253, 49
	s_mov_b64 s[28:29], 0
	s_nop 0
	v_mov_b64_e32 v[2:3], s[0:1]
	flat_load_dword v2, v[2:3] sc1
	s_waitcnt vmcnt(0) lgkmcnt(0)
	v_cmp_eq_u32_e32 vcc, v2, v1
	s_and_saveexec_b64 s[22:23], vcc
	s_cbranch_execz .LBB0_231
	s_mov_b32 s0, 1
	s_branch .LBB0_224

; DI unsigned xb_ld(unsigned* p)              { return __hip_atomic_load(p, __ATOMIC_RELAXED, __HIP_MEMORY_SCOPE_AGENT); }
; DI unsigned xb_add(unsigned* p, unsigned v) { return __hip_atomic_fetch_add(p, v, __ATOMIC_RELAXED, __HIP_MEMORY_SCOPE_AGENT); }
; #define XB_SPIN(cond, bar) do { unsigned _sp = 0; while (cond) { __builtin_amdgcn_s_sleep(1); \
;     if ((++_sp & 255u) == 0u) { if (xb_ld(&(bar)[XB_TMO])) break; if (_sp > XB_SPIN_CAP) { atomicAdd(&(bar)[XB_TMO], 1u); break; } } } } while (0)
; DI void xcd_barrier(const XcdBarrier& b) {
;     ...
;             if (og + 1u == (tg + 1u) * nx) xb_add(&bar[XB_TOPGEN], 1u);
;             else XB_SPIN(xb_ld(&bar[XB_TOPGEN]) == tg, bar);
.LBB0_229:
	v_readlane_b32 s24, v253, 48
	v_readlane_b32 s25, v253, 49
	s_add_i32 s0, s0, 1
	s_or_b64 s[36:37], s[36:37], exec
	v_mov_b64_e32 v[2:3], s[24:25]
	flat_load_dword v2, v[2:3] sc1
	s_waitcnt vmcnt(0) lgkmcnt(0)
	v_cmp_ne_u32_e32 vcc, v2, v1
	s_orn2_b64 s[34:35], vcc, exec
	s_branch .LBB0_223

; DI unsigned xb_add(unsigned* p, unsigned v) { return __hip_atomic_fetch_add(p, v, __ATOMIC_RELAXED, __HIP_MEMORY_SCOPE_AGENT); }
; DI void xcd_barrier(const XcdBarrier& b) {
;     ...
;             __builtin_amdgcn_fence(__ATOMIC_ACQUIRE, "agent");
;             xb_add(&bar[XB_XGEN(b.x)], 1u);
;             asm volatile("s_waitcnt vmcnt(0)" ::: "memory");
.LBB0_234:
	s_or_b64 exec, exec, s[18:19]
	v_readlane_b32 s0, v253, 48
	v_readlane_b32 s1, v253, 49
	s_waitcnt vmcnt(0) lgkmcnt(0)
	buffer_inv sc1
	v_mov_b64_e32 v[2:3], s[0:1]
	s_waitcnt vmcnt(0)

; DI unsigned xb_ld(unsigned* p)              { return __hip_atomic_load(p, __ATOMIC_RELAXED, __HIP_MEMORY_SCOPE_AGENT); }
; DI unsigned xb_add(unsigned* p, unsigned v) { return __hip_atomic_fetch_add(p, v, __ATOMIC_RELAXED, __HIP_MEMORY_SCOPE_AGENT); }
; #define XB_SPIN(cond, bar) do { unsigned _sp = 0; while (cond) { __builtin_amdgcn_s_sleep(1); \
;     if ((++_sp & 255u) == 0u) { if (xb_ld(&(bar)[XB_TMO])) break; if (_sp > XB_SPIN_CAP) { atomicAdd(&(bar)[XB_TMO], 1u); break; } } } } while (0)
; DI void xcd_barrier(const XcdBarrier& b) {
;     ...
;             if (og + 1u == (tg + 1u) * nx) xb_add(&bar[XB_TOPGEN], 1u);
;             else XB_SPIN(xb_ld(&bar[XB_TOPGEN]) == tg, bar);
.Lxb_nl_2:
	v_readlane_b32 s0, v253, 48
	v_readlane_b32 s1, v253, 49
	s_mov_b64 s[26:27], 0
	s_nop 0
	v_mov_b64_e32 v[2:3], s[0:1]
	flat_load_dword v2, v[2:3] sc1
	s_waitcnt vmcnt(0) lgkmcnt(0)
	v_cmp_eq_u32_e32 vcc, v2, v1
	s_and_saveexec_b64 s[22:23], vcc
	s_cbranch_execz .LBB0_324
	s_mov_b32 s0, 1
	s_branch .LBB0_317

; DI unsigned xb_ld(unsigned* p)              { return __hip_atomic_load(p, __ATOMIC_RELAXED, __HIP_MEMORY_SCOPE_AGENT); }
; DI unsigned xb_add(unsigned* p, unsigned v) { return __hip_atomic_fetch_add(p, v, __ATOMIC_RELAXED, __HIP_MEMORY_SCOPE_AGENT); }
; #define XB_SPIN(cond, bar) do { unsigned _sp = 0; while (cond) { __builtin_amdgcn_s_sleep(1); \
;     if ((++_sp & 255u) == 0u) { if (xb_ld(&(bar)[XB_TMO])) break; if (_sp > XB_SPIN_CAP) { atomicAdd(&(bar)[XB_TMO], 1u); break; } } } } while (0)
; DI void xcd_barrier(const XcdBarrier& b) {
;     ...
;             if (og + 1u == (tg + 1u) * nx) xb_add(&bar[XB_TOPGEN], 1u);
;             else XB_SPIN(xb_ld(&bar[XB_TOPGEN]) == tg, bar);
.LBB0_322:
	v_readlane_b32 s24, v253, 48
	v_readlane_b32 s25, v253, 49
	s_add_i32 s0, s0, 1
	s_or_b64 s[34:35], s[34:35], exec
	v_mov_b64_e32 v[2:3], s[24:25]
	flat_load_dword v2, v[2:3] sc1
	s_waitcnt vmcnt(0) lgkmcnt(0)
	v_cmp_ne_u32_e32 vcc, v2, v1
	s_orn2_b64 s[30:31], vcc, exec
	s_branch .LBB0_316

; DI unsigned xb_ld(unsigned* p)              { return __hip_atomic_load(p, __ATOMIC_RELAXED, __HIP_MEMORY_SCOPE_AGENT); }
; DI unsigned xb_add(unsigned* p, unsigned v) { return __hip_atomic_fetch_add(p, v, __ATOMIC_RELAXED, __HIP_MEMORY_SCOPE_AGENT); }
; #define XB_SPIN(cond, bar) do { unsigned _sp = 0; while (cond) { __builtin_amdgcn_s_sleep(1); \
;     if ((++_sp & 255u) == 0u) { if (xb_ld(&(bar)[XB_TMO])) break; if (_sp > XB_SPIN_CAP) { atomicAdd(&(bar)[XB_TMO], 1u); break; } } } } while (0)
; DI void xcd_barrier(const XcdBarrier& b) {
;     ...
;         const unsigned old = xb_add(&bar[XB_XSUB(b.x)], 1u);
;         const unsigned gen = old / nloc;
;         if (old + 1u == (gen + 1u) * nloc) {
;             __builtin_amdgcn_fence(__ATOMIC_RELEASE, "agent");
;             asm volatile("s_waitcnt vmcnt(0)" ::: "memory");
;             const unsigned og = xb_add(&bar[XB_TOP], 1u);
;             const unsigned tg = og / nx;
;             if (og + 1u == (tg + 1u) * nx) xb_add(&bar[XB_TOPGEN], 1u);
;             else XB_SPIN(xb_ld(&bar[XB_TOPGEN]) == tg, bar);
.LBB0_372:
	s_andn2_saveexec_b64 s[18:19], s[18:19]
	s_cbranch_execz .LBB0_388
	v_readlane_b32 s18, v253, 50
	v_readlane_b32 s19, v253, 51
	buffer_wbl2 sc1
	s_waitcnt vmcnt(0)
	v_cvt_f32_u32_e32 v1, v2
	v_mov_b64_e32 v[4:5], s[18:19]
	flat_atomic_add v3, v[4:5], v223 sc0
	v_sub_u32_e32 v4, 0, v2
	v_rcp_iflag_f32_e32 v1, v1
	s_mov_b64 s[22:23], -1
	v_mul_f32_e32 v1, 0x4f7ffffe, v1
	v_cvt_u32_f32_e32 v1, v1
	v_mul_lo_u32 v4, v4, v1
	v_mul_hi_u32 v4, v1, v4
	v_add_u32_e32 v1, v1, v4
	s_waitcnt vmcnt(0) lgkmcnt(0)
	v_mul_hi_u32 v1, v3, v1
	v_mul_lo_u32 v4, v1, v2
	v_sub_u32_e32 v4, v3, v4
	v_cmp_ge_u32_e32 vcc, v4, v2
	v_add_u32_e32 v5, 1, v1
	s_nop 0
	v_cndmask_b32_e32 v1, v1, v5, vcc
	v_sub_u32_e32 v5, v4, v2
	v_cndmask_b32_e32 v4, v4, v5, vcc
	v_cmp_ge_u32_e32 vcc, v4, v2
	v_add_u32_e32 v4, 1, v1
	s_nop 0
	v_cndmask_b32_e32 v1, v1, v4, vcc
	v_add_u32_e32 v4, 1, v3
	v_mad_u64_u32 v[2:3], s[18:19], v2, v1, v[2:3]
	v_readlane_b32 s18, v253, 52
	v_readlane_b32 s19, v253, 53
	v_cmp_ne_u32_e32 vcc, v4, v2
	s_nop 0
	v_mov_b64_e32 v[2:3], s[18:19]
	s_and_saveexec_b64 s[18:19], vcc
	s_cbranch_execnz .Lxb_nl_3
	s_mov_b64 exec, s[18:19]
	v_add_co_u32_e32 v4, vcc, 0xffffef00, v2
	s_nop 1
	v_addc_co_u32_e32 v5, vcc, -1, v3, vcc
	s_nop 1
	global_atomic_add v[4:5], v223, off
	global_atomic_add v[4:5], v223, off offset:256
	global_atomic_add v[4:5], v223, off offset:512
	global_atomic_add v[4:5], v223, off offset:768
	global_atomic_add v[4:5], v223, off offset:1024
	global_atomic_add v[4:5], v223, off offset:1280
	global_atomic_add v[4:5], v223, off offset:1536
	global_atomic_add v[4:5], v223, off offset:1792
	global_atomic_add v[4:5], v223, off offset:2048
	global_atomic_add v[4:5], v223, off offset:2304
	global_atomic_add v[4:5], v223, off offset:2560
	global_atomic_add v[4:5], v223, off offset:2816
	global_atomic_add v[4:5], v223, off offset:3072
	global_atomic_add v[4:5], v223, off offset:3328
	global_atomic_add v[4:5], v223, off offset:3584
	global_atomic_add v[4:5], v223, off offset:3840
	s_mov_b64 exec, 0
	s_branch .LBB0_385
.Lxb_nl_3:
	v_readlane_b32 s22, v253, 48
	v_readlane_b32 s23, v253, 49
	s_mov_b64 s[26:27], 0
	s_nop 0
	v_mov_b64_e32 v[2:3], s[22:23]
	flat_load_dword v2, v[2:3] sc1
	s_waitcnt vmcnt(0) lgkmcnt(0)
	v_cmp_eq_u32_e32 vcc, v2, v1
	s_and_saveexec_b64 s[22:23], vcc
	s_cbranch_execz .LBB0_384
	s_mov_b32 s2, 1
	s_branch .LBB0_377

; DI unsigned xb_ld(unsigned* p)              { return __hip_atomic_load(p, __ATOMIC_RELAXED, __HIP_MEMORY_SCOPE_AGENT); }
; DI unsigned xb_add(unsigned* p, unsigned v) { return __hip_atomic_fetch_add(p, v, __ATOMIC_RELAXED, __HIP_MEMORY_SCOPE_AGENT); }
; #define XB_SPIN(cond, bar) do { unsigned _sp = 0; while (cond) { __builtin_amdgcn_s_sleep(1); \
;     if ((++_sp & 255u) == 0u) { if (xb_ld(&(bar)[XB_TMO])) break; if (_sp > XB_SPIN_CAP) { atomicAdd(&(bar)[XB_TMO], 1u); break; } } } } while (0)
; DI void xcd_barrier(const XcdBarrier& b) {
;     ...
;             if (og + 1u == (tg + 1u) * nx) xb_add(&bar[XB_TOPGEN], 1u);
;             else XB_SPIN(xb_ld(&bar[XB_TOPGEN]) == tg, bar);
.LBB0_382:
	v_readlane_b32 s30, v253, 48
	v_readlane_b32 s31, v253, 49
	s_add_i32 s2, s2, 1
	s_or_b64 s[34:35], s[34:35], exec
	v_mov_b64_e32 v[2:3], s[30:31]
	flat_load_dword v2, v[2:3] sc1
	s_waitcnt vmcnt(0) lgkmcnt(0)
	v_cmp_ne_u32_e32 vcc, v2, v1
	s_orn2_b64 s[30:31], vcc, exec
	s_branch .LBB0_376

; DI unsigned xb_ld(unsigned* p)              { return __hip_atomic_load(p, __ATOMIC_RELAXED, __HIP_MEMORY_SCOPE_AGENT); }
; DI unsigned xb_add(unsigned* p, unsigned v) { return __hip_atomic_fetch_add(p, v, __ATOMIC_RELAXED, __HIP_MEMORY_SCOPE_AGENT); }
; #define XB_SPIN(cond, bar) do { unsigned _sp = 0; while (cond) { __builtin_amdgcn_s_sleep(1); \
;     if ((++_sp & 255u) == 0u) { if (xb_ld(&(bar)[XB_TMO])) break; if (_sp > XB_SPIN_CAP) { atomicAdd(&(bar)[XB_TMO], 1u); break; } } } } while (0)
; DI void xcd_barrier(const XcdBarrier& b) {
;     ...
;         const unsigned old = xb_add(&bar[XB_XSUB(b.x)], 1u);
;         const unsigned gen = old / nloc;
;         if (old + 1u == (gen + 1u) * nloc) {
;             __builtin_amdgcn_fence(__ATOMIC_RELEASE, "agent");
;             asm volatile("s_waitcnt vmcnt(0)" ::: "memory");
;             const unsigned og = xb_add(&bar[XB_TOP], 1u);
;             const unsigned tg = og / nx;
;             if (og + 1u == (tg + 1u) * nx) xb_add(&bar[XB_TOPGEN], 1u);
;             else XB_SPIN(xb_ld(&bar[XB_TOPGEN]) == tg, bar);
.LBB0_597:
	s_andn2_saveexec_b64 s[18:19], s[18:19]
	s_cbranch_execz .LBB0_613
	v_readlane_b32 s18, v253, 50
	v_readlane_b32 s19, v253, 51
	buffer_wbl2 sc1
	s_waitcnt vmcnt(0)
	v_cvt_f32_u32_e32 v1, v2
	v_mov_b64_e32 v[4:5], s[18:19]
	flat_atomic_add v3, v[4:5], v223 sc0
	v_sub_u32_e32 v4, 0, v2
	v_rcp_iflag_f32_e32 v1, v1
	s_mov_b64 s[20:21], -1
	v_mul_f32_e32 v1, 0x4f7ffffe, v1
	v_cvt_u32_f32_e32 v1, v1
	v_mul_lo_u32 v4, v4, v1
	v_mul_hi_u32 v4, v1, v4
	v_add_u32_e32 v1, v1, v4
	s_waitcnt vmcnt(0) lgkmcnt(0)
	v_mul_hi_u32 v1, v3, v1
	v_mul_lo_u32 v4, v1, v2
	v_sub_u32_e32 v4, v3, v4
	v_cmp_ge_u32_e32 vcc, v4, v2
	v_add_u32_e32 v5, 1, v1
	s_nop 0
	v_cndmask_b32_e32 v1, v1, v5, vcc
	v_sub_u32_e32 v5, v4, v2
	v_cndmask_b32_e32 v4, v4, v5, vcc
	v_cmp_ge_u32_e32 vcc, v4, v2
	v_add_u32_e32 v4, 1, v1
	s_nop 0
	v_cndmask_b32_e32 v1, v1, v4, vcc
	v_add_u32_e32 v4, 1, v3
	v_mad_u64_u32 v[2:3], s[18:19], v2, v1, v[2:3]
	v_readlane_b32 s18, v253, 52
	v_readlane_b32 s19, v253, 53
	v_cmp_ne_u32_e32 vcc, v4, v2
	s_nop 0
	v_mov_b64_e32 v[2:3], s[18:19]
	s_and_saveexec_b64 s[18:19], vcc
	s_cbranch_execnz .Lxb_nl_4
	s_mov_b64 exec, s[18:19]
	v_add_co_u32_e32 v4, vcc, 0xffffef00, v2
	s_nop 1
	v_addc_co_u32_e32 v5, vcc, -1, v3, vcc
	s_nop 1
	global_atomic_add v[4:5], v223, off
	global_atomic_add v[4:5], v223, off offset:256
	global_atomic_add v[4:5], v223, off offset:512
	global_atomic_add v[4:5], v223, off offset:768
	global_atomic_add v[4:5], v223, off offset:1024
	global_atomic_add v[4:5], v223, off offset:1280
	global_atomic_add v[4:5], v223, off offset:1536
	global_atomic_add v[4:5], v223, off offset:1792
	global_atomic_add v[4:5], v223, off offset:2048
	global_atomic_add v[4:5], v223, off offset:2304
	global_atomic_add v[4:5], v223, off offset:2560
	global_atomic_add v[4:5], v223, off offset:2816
	global_atomic_add v[4:5], v223, off offset:3072
	global_atomic_add v[4:5], v223, off offset:3328
	global_atomic_add v[4:5], v223, off offset:3584
	global_atomic_add v[4:5], v223, off offset:3840
	s_mov_b64 exec, 0
	s_branch .LBB0_610

; DI unsigned xb_ld(unsigned* p)              { return __hip_atomic_load(p, __ATOMIC_RELAXED, __HIP_MEMORY_SCOPE_AGENT); }
; DI unsigned xb_add(unsigned* p, unsigned v) { return __hip_atomic_fetch_add(p, v, __ATOMIC_RELAXED, __HIP_MEMORY_SCOPE_AGENT); }
; #define XB_SPIN(cond, bar) do { unsigned _sp = 0; while (cond) { __builtin_amdgcn_s_sleep(1); \
;     if ((++_sp & 255u) == 0u) { if (xb_ld(&(bar)[XB_TMO])) break; if (_sp > XB_SPIN_CAP) { atomicAdd(&(bar)[XB_TMO], 1u); break; } } } } while (0)
; DI void xcd_barrier(const XcdBarrier& b) {
;     ...
;         const unsigned old = xb_add(&bar[XB_XSUB(b.x)], 1u);
;         const unsigned gen = old / nloc;
;         if (old + 1u == (gen + 1u) * nloc) {
;             __builtin_amdgcn_fence(__ATOMIC_RELEASE, "agent");
;             asm volatile("s_waitcnt vmcnt(0)" ::: "memory");
;             const unsigned og = xb_add(&bar[XB_TOP], 1u);
;             const unsigned tg = og / nx;
;             if (og + 1u == (tg + 1u) * nx) xb_add(&bar[XB_TOPGEN], 1u);
;             else XB_SPIN(xb_ld(&bar[XB_TOPGEN]) == tg, bar);
.LBB0_2327:
	v_readlane_b32 s18, v253, 50
	v_readlane_b32 s19, v253, 51
	buffer_wbl2 sc1
	s_waitcnt vmcnt(0)
	v_cvt_f32_u32_e32 v1, v2
	v_mov_b64_e32 v[4:5], s[18:19]
	flat_atomic_add v3, v[4:5], v223 sc0
	v_sub_u32_e32 v4, 0, v2
	v_rcp_iflag_f32_e32 v1, v1
	s_mov_b64 s[20:21], -1
	v_mul_f32_e32 v1, 0x4f7ffffe, v1
	v_cvt_u32_f32_e32 v1, v1
	v_mul_lo_u32 v4, v4, v1
	v_mul_hi_u32 v4, v1, v4
	v_add_u32_e32 v1, v1, v4
	s_waitcnt vmcnt(0) lgkmcnt(0)
	v_mul_hi_u32 v1, v3, v1
	v_mul_lo_u32 v4, v1, v2
	v_sub_u32_e32 v4, v3, v4
	v_cmp_ge_u32_e32 vcc, v4, v2
	v_add_u32_e32 v5, 1, v1
	s_nop 0
	v_cndmask_b32_e32 v1, v1, v5, vcc
	v_sub_u32_e32 v5, v4, v2
	v_cndmask_b32_e32 v4, v4, v5, vcc
	v_cmp_ge_u32_e32 vcc, v4, v2
	v_add_u32_e32 v4, 1, v1
	s_nop 0
	v_cndmask_b32_e32 v1, v1, v4, vcc
	v_add_u32_e32 v4, 1, v3
	v_mad_u64_u32 v[2:3], s[18:19], v2, v1, v[2:3]
	v_readlane_b32 s18, v253, 52
	v_readlane_b32 s19, v253, 53
	v_cmp_ne_u32_e32 vcc, v4, v2
	s_nop 0
	v_mov_b64_e32 v[2:3], s[18:19]
	s_and_saveexec_b64 s[18:19], vcc
	s_cbranch_execnz .Lxb_nl_14
	s_mov_b64 exec, s[18:19]
	v_add_co_u32_e32 v4, vcc, 0xffffef00, v2
	s_nop 1
	v_addc_co_u32_e32 v5, vcc, -1, v3, vcc
	s_nop 1
	global_atomic_add v[4:5], v223, off
	global_atomic_add v[4:5], v223, off offset:256
	global_atomic_add v[4:5], v223, off offset:512
	global_atomic_add v[4:5], v223, off offset:768
	global_atomic_add v[4:5], v223, off offset:1024
	global_atomic_add v[4:5], v223, off offset:1280
	global_atomic_add v[4:5], v223, off offset:1536
	global_atomic_add v[4:5], v223, off offset:1792
	global_atomic_add v[4:5], v223, off offset:2048
	global_atomic_add v[4:5], v223, off offset:2304
	global_atomic_add v[4:5], v223, off offset:2560
	global_atomic_add v[4:5], v223, off offset:2816
	global_atomic_add v[4:5], v223, off offset:3072
	global_atomic_add v[4:5], v223, off offset:3328
	global_atomic_add v[4:5], v223, off offset:3584
	global_atomic_add v[4:5], v223, off offset:3840
	s_mov_b64 exec, 0
	s_branch .LBB0_2339
